# branch epilogue: 16 gate loads per n issued together; out epilogue: residual x loads issued in two batches of 8 and per-group store-drain waits removed
# speedup vs baseline: 1.0254x; 1.0116x over previous
; #define MFMA32(a, b, c) __builtin_amdgcn_mfma_f32_32x32x16_bf16((a), (b), (c), 0, 0, 0)
; DI f32x16 zero16() { f32x16 z; _Pragma("unroll") for (int i = 0; i < 16; ++i) z[i] = 0.f; return z; }
; #define G_LOAD(KOFF) do { rw0 = *(const uint4*)(gw + (KOFF)); rw1 = *(const uint4*)(gw1 + (KOFF)); rw2 = *(const uint4*)(gw2 + (KOFF)); rw3 = *(const uint4*)(gw3 + (KOFF)); \
;                           rx0 = *(const uint4*)(gx + (KOFF)); rx1 = *(const uint4*)(gx1 + (KOFF)); rx2 = *(const uint4*)(gx2 + (KOFF)); rx3 = *(const uint4*)(gx3 + (KOFF)); } while (0)
; DI void gemm128(const u16* __restrict__ W, int ldw, const u16* __restrict__ X, int ldx, int K, f32x16 (&acc)[2][2], char* smem) {
;     ...
;   for (int kt = 0; kt < nk; ++kt) {
;     const int buf = kt & 1;
; #pragma unroll
;     for (int ks = 0; ks < 4; ++ks) {
;       bf16x8 a0 = *(const bf16x8*)&sw[buf][wn * 64 + r][ks * 16 + h * 8];
;       bf16x8 a1 = *(const bf16x8*)&sw[buf][wn * 64 + 32 + r][ks * 16 + h * 8];
;       bf16x8 b0 = *(const bf16x8*)&sx[buf][wm * 64 + r][ks * 16 + h * 8];
;       bf16x8 b1 = *(const bf16x8*)&sx[buf][wm * 64 + 32 + r][ks * 16 + h * 8];
;       acc[0][0] = MFMA32(a0, b0, acc[0][0]);
;       acc[0][1] = MFMA32(a0, b1, acc[0][1]);
;       acc[1][0] = MFMA32(a1, b0, acc[1][0]);
;       acc[1][1] = MFMA32(a1, b1, acc[1][1]);
;     }
;     if (kt + 1 < nk) G_STORE(buf ^ 1);
;     if (kt + 2 < nk) G_LOAD((kt + 2) * 64);
;     __syncthreads();
;   }
; DI void phase_branch(const Params& p, int layer, char* smem, int xcd, int loc, int nloc) {
;     ...
;     for (int n = 0; n < 3; ++n) {
;       f32x16 acc[2][2];
;       acc[0][0] = zero16(); acc[0][1] = zero16(); acc[1][0] = zero16(); acc[1][1] = zero16();
;       gemm128(WBR + ((size_t)n * 1024 + d0) * LDB, LDB, YBR + (size_t)m0 * LDY + n * 512, LDY, 512, acc, smem);
;       const float* gb = p.gate_b + ((size_t)layer * 3 + n) * 1024;
.LBB0_19:
	s_and_b32 s45, s44, 1
	s_mul_i32 s46, s45, 0x4800
	v_add_u32_e32 v2, s46, v230
	ds_read_b128 v[232:235], v2 offset:4608
	v_add_u32_e32 v231, s46, v197
	ds_read_b128 v[236:239], v231 offset:41472
	ds_read_b128 v[240:243], v2
	ds_read_b128 v[244:247], v2 offset:32
	ds_read_b128 v[248:251], v231 offset:36864
	ds_read_b128 v[130:133], v231 offset:36896
	s_waitcnt lgkmcnt(3)
	v_mfma_f32_32x32x16_bf16 v[20:35], v[240:243], v[236:239], v[20:35]
	s_xor_b32 s45, s45, 1
	s_mulk_i32 s45, 0x4800
	s_add_i32 s44, s44, 1
	s_waitcnt lgkmcnt(1)
	v_mfma_f32_32x32x16_bf16 v[52:67], v[240:243], v[248:251], v[52:67]
	v_mfma_f32_32x32x16_bf16 v[36:51], v[232:235], v[248:251], v[36:51]
	v_mfma_f32_32x32x16_bf16 v[4:19], v[232:235], v[236:239], v[4:19]
	ds_read_b128 v[232:235], v2 offset:4640
	ds_read_b128 v[236:239], v231 offset:41504
	s_waitcnt lgkmcnt(2)
	v_mfma_f32_32x32x16_bf16 v[52:67], v[244:247], v[130:133], v[52:67]
	s_waitcnt lgkmcnt(0)
	v_mfma_f32_32x32x16_bf16 v[20:35], v[244:247], v[236:239], v[20:35]
	v_mfma_f32_32x32x16_bf16 v[36:51], v[232:235], v[130:133], v[36:51]
	v_mfma_f32_32x32x16_bf16 v[4:19], v[232:235], v[236:239], v[4:19]
	ds_read_b128 v[130:133], v2 offset:64
	ds_read_b128 v[232:235], v2 offset:4672
	ds_read_b128 v[236:239], v231 offset:36928
	ds_read_b128 v[240:243], v231 offset:41536
	s_waitcnt lgkmcnt(1)
	v_mfma_f32_32x32x16_bf16 v[52:67], v[130:133], v[236:239], v[52:67]
	s_waitcnt lgkmcnt(0)
	v_mfma_f32_32x32x16_bf16 v[20:35], v[130:133], v[240:243], v[20:35]
	v_mfma_f32_32x32x16_bf16 v[36:51], v[232:235], v[236:239], v[36:51]
	v_mfma_f32_32x32x16_bf16 v[4:19], v[232:235], v[240:243], v[4:19]
	ds_read_b128 v[130:133], v2 offset:96
	ds_read_b128 v[232:235], v2 offset:4704
	ds_read_b128 v[236:239], v231 offset:36960
	ds_read_b128 v[240:243], v231 offset:41568
	v_add_u32_e32 v2, s45, v196
	s_waitcnt vmcnt(7)
	ds_write_b128 v2, v[68:71]
	s_waitcnt vmcnt(6)
	ds_write_b128 v2, v[72:75] offset:4608
	s_waitcnt vmcnt(5)
	ds_write_b128 v2, v[76:79] offset:9216
	s_waitcnt vmcnt(4)
	ds_write_b128 v2, v[80:83] offset:13824
	s_waitcnt vmcnt(3)
	ds_write_b128 v2, v[84:87] offset:36864
	s_waitcnt vmcnt(2)
	ds_write_b128 v2, v[88:91] offset:41472
	s_waitcnt vmcnt(1)
	ds_write_b128 v2, v[92:95] offset:46080
	s_waitcnt vmcnt(0)
	ds_write_b128 v2, v[96:99] offset:50688
	v_lshl_add_u64 v[80:81], v[200:201], 0, s[12:13]
	s_mov_b32 s45, 0x104c000
	v_add_co_u32_e32 v68, vcc, s45, v80
	s_mov_b32 s45, 0x1055000
	s_nop 0
	v_addc_co_u32_e32 v69, vcc, 0, v81, vcc
	v_add_co_u32_e32 v72, vcc, s45, v80
	s_mov_b32 s45, 0x105e000
	s_nop 0
	v_addc_co_u32_e32 v73, vcc, 0, v81, vcc
	v_add_co_u32_e32 v76, vcc, s45, v80
	s_mov_b32 s45, 0x1067000
	s_nop 0
	v_addc_co_u32_e32 v77, vcc, 0, v81, vcc
	v_add_co_u32_e32 v80, vcc, s45, v80
	v_lshl_add_u64 v[96:97], v[198:199], 0, s[12:13]
	s_nop 0
	v_addc_co_u32_e32 v81, vcc, 0, v81, vcc
	v_add_co_u32_e32 v84, vcc, s3, v96
	s_mov_b32 s45, 0x15cb1000
	s_nop 0
	v_addc_co_u32_e32 v85, vcc, 0, v97, vcc
	v_add_co_u32_e32 v88, vcc, s45, v96
	s_mov_b32 s45, 0x15cca000
	s_nop 0
	v_addc_co_u32_e32 v89, vcc, 0, v97, vcc
	v_add_co_u32_e32 v92, vcc, s45, v96
	s_mov_b32 s45, 0x15ce3000
	s_nop 0
	v_addc_co_u32_e32 v93, vcc, 0, v97, vcc
	v_add_co_u32_e32 v96, vcc, s45, v96
	global_load_dwordx4 v[68:71], v[68:69], off offset:256
	s_nop 0
	v_addc_co_u32_e32 v97, vcc, 0, v97, vcc
	global_load_dwordx4 v[72:75], v[72:73], off offset:256
	s_waitcnt lgkmcnt(9)
	v_mfma_f32_32x32x16_bf16 v[52:67], v[130:133], v[236:239], v[52:67]
	global_load_dwordx4 v[76:79], v[76:77], off offset:256
	s_add_u32 s12, s12, 0x80
	global_load_dwordx4 v[80:83], v[80:81], off offset:256
	s_addc_u32 s13, s13, 0
	global_load_dwordx4 v[84:87], v[84:85], off offset:256
	s_cmpk_eq_i32 s12, 0x300
	global_load_dwordx4 v[88:91], v[88:89], off offset:256
	s_waitcnt lgkmcnt(8)
	v_mfma_f32_32x32x16_bf16 v[20:35], v[130:133], v[240:243], v[20:35]
	global_load_dwordx4 v[92:95], v[92:93], off offset:256
	s_nop 0
	global_load_dwordx4 v[96:99], v[96:97], off offset:256
	s_waitcnt lgkmcnt(0)
	s_barrier
	v_mfma_f32_32x32x16_bf16 v[36:51], v[232:235], v[236:239], v[36:51]
	v_mfma_f32_32x32x16_bf16 v[4:19], v[232:235], v[240:243], v[4:19]
	s_cbranch_scc0 .LBB0_19
	ds_read_b128 v[198:201], v230 offset:4608
	ds_read_b128 v[232:235], v197 offset:41472
	ds_read_b128 v[236:239], v230
	ds_read_b128 v[240:243], v230 offset:32
	ds_read_b128 v[244:247], v197 offset:36864
	ds_read_b128 v[248:251], v197 offset:36896
	s_waitcnt lgkmcnt(4)
	v_mfma_f32_32x32x16_bf16 v[4:19], v[198:201], v[232:235], v[4:19]
	v_add_u32_e32 v2, 0xd800, v196
	s_add_u32 s12, s16, s28
	s_addc_u32 s13, 0, s29
	s_lshl_b64 s[44:45], s[12:13], 12
	s_lshl_b32 s12, s16, 11
	s_mov_b32 s13, s17
	s_add_i32 s16, s16, 1
	s_waitcnt lgkmcnt(3)
	v_mfma_f32_32x32x16_bf16 v[20:35], v[236:239], v[232:235], v[20:35]
	s_add_u32 s6, s6, 0x400
	s_addc_u32 s7, s7, 0
	s_add_u32 s10, s10, 0x120000
	s_addc_u32 s11, s11, 0
	s_cmp_eq_u32 s16, 3
	s_waitcnt lgkmcnt(1)
	v_mfma_f32_32x32x16_bf16 v[52:67], v[236:239], v[244:247], v[52:67]
	v_mfma_f32_32x32x16_bf16 v[36:51], v[198:201], v[244:247], v[36:51]
	ds_read_b128 v[198:201], v230 offset:4640
	ds_read_b128 v[232:235], v197 offset:41504
	s_waitcnt lgkmcnt(0)
	v_mfma_f32_32x32x16_bf16 v[20:35], v[240:243], v[232:235], v[20:35]
	v_mfma_f32_32x32x16_bf16 v[4:19], v[198:201], v[232:235], v[4:19]
	v_mfma_f32_32x32x16_bf16 v[52:67], v[240:243], v[248:251], v[52:67]
	v_mfma_f32_32x32x16_bf16 v[36:51], v[198:201], v[248:251], v[36:51]
	ds_read_b128 v[198:201], v230 offset:64
	ds_read_b128 v[232:235], v230 offset:4672
	ds_read_b128 v[236:239], v197 offset:36928
	ds_read_b128 v[240:243], v197 offset:41536
	s_waitcnt lgkmcnt(0)
	v_mfma_f32_32x32x16_bf16 v[20:35], v[198:201], v[240:243], v[20:35]
	v_mfma_f32_32x32x16_bf16 v[4:19], v[232:235], v[240:243], v[4:19]
	v_mfma_f32_32x32x16_bf16 v[52:67], v[198:201], v[236:239], v[52:67]
	v_mfma_f32_32x32x16_bf16 v[36:51], v[232:235], v[236:239], v[36:51]
	ds_read_b128 v[198:201], v230 offset:96
	ds_read_b128 v[232:235], v230 offset:4704
	ds_read_b128 v[236:239], v197 offset:36960
	ds_read_b128 v[240:243], v197 offset:41568
	s_waitcnt vmcnt(7)
	ds_write_b128 v196, v[68:71] offset:18432
	s_waitcnt vmcnt(6)
	ds_write_b128 v196, v[72:75] offset:23040
	s_waitcnt vmcnt(5)
	ds_write_b128 v196, v[76:79] offset:27648
	s_waitcnt vmcnt(4)
	ds_write_b128 v196, v[80:83] offset:32256
	s_waitcnt vmcnt(3)
	ds_write_b128 v196, v[84:87] offset:55296
	s_waitcnt vmcnt(2)
	ds_write_b128 v196, v[88:91] offset:59904
	s_waitcnt vmcnt(1)
	ds_write_b128 v196, v[92:95] offset:64512
	s_waitcnt vmcnt(0)
	ds_write_b128 v2, v[96:99] offset:13824
	s_waitcnt lgkmcnt(0)
	s_barrier
; DI float bflo(uint32_t u) { return __uint_as_float(u << 16); }
; DI float bfhi(uint32_t u) { return __uint_as_float(u & 0xffff0000u); }
; DI float fsigmoid(float x) { return frcp(1.f + fexp2(-LOG2E * x)); }
; DI void phase_branch(const Params& p, int layer, char* smem, int xcd, int loc, int nloc) {
;     ...
;       for (int mi = 0; mi < 2; ++mi) {
;         const int m = m0 + wm * 64 + mi * 32 + r;
; #pragma unroll
;         for (int ni = 0; ni < 2; ++ni)
; #pragma unroll
;           for (int g = 0; g < 4; ++g) {
;             const int d4 = d0 + wn * 64 + ni * 32 + 8 * g + 4 * h;
;             uint2 gu = *(const uint2*)(PROJ + (size_t)m * LDP + O_G + n * 1024 + d4);
;             float4 bb = *(const float4*)(gb + d4);
;             float g0 = bflo(gu.x) + bb.x, g1 = bfhi(gu.x) + bb.y, g2 = bflo(gu.y) + bb.z, g3 = bfhi(gu.y) + bb.w;
;             sum[ni][mi][4 * g] += acc[ni][mi][4 * g] * fsigmoid(g0);
;             sum[ni][mi][4 * g + 1] += acc[ni][mi][4 * g + 1] * fsigmoid(g1);
;             sum[ni][mi][4 * g + 2] += acc[ni][mi][4 * g + 2] * fsigmoid(g2);
;             sum[ni][mi][4 * g + 3] += acc[ni][mi][4 * g + 3] * fsigmoid(g3);
;           }
	ds_read_b128 v[68:71], v230 offset:23040
	ds_read_b128 v[72:75], v197 offset:59904
	ds_read_b128 v[76:79], v230 offset:18432
	ds_read_b128 v[80:83], v230 offset:18464
	ds_read_b128 v[84:87], v197 offset:55296
	ds_read_b128 v[88:91], v197 offset:55328
	v_mfma_f32_32x32x16_bf16 v[20:35], v[198:201], v[240:243], v[20:35]
	v_mfma_f32_32x32x16_bf16 v[4:19], v[232:235], v[240:243], v[4:19]
	v_mfma_f32_32x32x16_bf16 v[52:67], v[198:201], v[236:239], v[52:67]
	v_mfma_f32_32x32x16_bf16 v[36:51], v[232:235], v[236:239], v[36:51]
	s_waitcnt lgkmcnt(3)
	v_mfma_f32_32x32x16_bf16 v[20:35], v[76:79], v[72:75], v[20:35]
	v_mfma_f32_32x32x16_bf16 v[4:19], v[68:71], v[72:75], v[4:19]
	s_waitcnt lgkmcnt(1)
	v_mfma_f32_32x32x16_bf16 v[52:67], v[76:79], v[84:87], v[52:67]
	v_mfma_f32_32x32x16_bf16 v[36:51], v[68:71], v[84:87], v[36:51]
	ds_read_b128 v[68:71], v230 offset:23072
	ds_read_b128 v[72:75], v197 offset:59936
	s_waitcnt lgkmcnt(0)
	v_mfma_f32_32x32x16_bf16 v[20:35], v[80:83], v[72:75], v[20:35]
	v_mfma_f32_32x32x16_bf16 v[4:19], v[68:71], v[72:75], v[4:19]
	v_mfma_f32_32x32x16_bf16 v[52:67], v[80:83], v[88:91], v[52:67]
	v_mfma_f32_32x32x16_bf16 v[36:51], v[68:71], v[88:91], v[36:51]
	ds_read_b128 v[68:71], v230 offset:18496
	ds_read_b128 v[72:75], v230 offset:23104
	ds_read_b128 v[76:79], v197 offset:55360
	ds_read_b128 v[80:83], v197 offset:59968
	s_waitcnt lgkmcnt(0)
	v_mfma_f32_32x32x16_bf16 v[20:35], v[68:71], v[80:83], v[20:35]
	v_mfma_f32_32x32x16_bf16 v[4:19], v[72:75], v[80:83], v[4:19]
	v_mfma_f32_32x32x16_bf16 v[52:67], v[68:71], v[76:79], v[52:67]
	v_mfma_f32_32x32x16_bf16 v[36:51], v[72:75], v[76:79], v[36:51]
	ds_read_b128 v[68:71], v230 offset:18528
	ds_read_b128 v[72:75], v230 offset:23136
	ds_read_b128 v[76:79], v197 offset:55392
	ds_read_b128 v[80:83], v197 offset:60000
	s_waitcnt lgkmcnt(0)
	s_barrier
	v_mfma_f32_32x32x16_bf16 v[20:35], v[68:71], v[80:83], v[20:35]
	v_mfma_f32_32x32x16_bf16 v[4:19], v[72:75], v[80:83], v[4:19]
	v_lshl_add_u64 v[82:83], v[122:123], 0, s[12:13]
	v_lshl_add_u64 v[80:81], v[124:125], 0, s[44:45]
	v_mfma_f32_32x32x16_bf16 v[52:67], v[68:71], v[76:79], v[52:67]
	v_lshl_add_u64 v[96:97], v[150:151], 0, s[12:13]
	global_load_dwordx2 v[98:99], v[82:83], off
	global_load_dwordx2 v[130:131], v[82:83], off offset:16
	global_load_dwordx2 v[132:133], v[82:83], off offset:32
	global_load_dwordx2 v[196:197], v[82:83], off offset:48
	global_load_dwordx2 v[198:199], v[82:83], off offset:64
	global_load_dwordx2 v[200:201], v[82:83], off offset:80
	global_load_dwordx2 v[230:231], v[82:83], off offset:96
	global_load_dwordx2 v[232:233], v[82:83], off offset:112
	global_load_dwordx2 v[234:235], v[96:97], off
	global_load_dwordx2 v[236:237], v[96:97], off offset:16
	global_load_dwordx2 v[238:239], v[96:97], off offset:32
	global_load_dwordx2 v[240:241], v[96:97], off offset:48
	global_load_dwordx2 v[242:243], v[96:97], off offset:64
	global_load_dwordx2 v[244:245], v[96:97], off offset:80
	global_load_dwordx2 v[246:247], v[96:97], off offset:96
	global_load_dwordx2 v[248:249], v[96:97], off offset:112
	s_waitcnt vmcnt(0)
	v_mov_b32_e32 v68, v98
	v_mov_b32_e32 v69, v99
	v_lshlrev_b32_e32 v2, 16, v68
	v_mfma_f32_32x32x16_bf16 v[36:51], v[72:75], v[76:79], v[36:51]
	global_load_dwordx4 v[76:79], v[80:81], off
	v_and_b32_e32 v68, 0xffff0000, v68
	s_waitcnt vmcnt(0)
	v_add_f32_e32 v2, v76, v2
	v_mul_f32_e32 v2, 0xbfb8aa3b, v2
	v_exp_f32_e32 v2, v2
	v_add_f32_e32 v70, v77, v68
	v_lshlrev_b32_e32 v68, 16, v69
	v_add_f32_e32 v71, v78, v68
	v_and_b32_e32 v68, 0xffff0000, v69
	v_add_f32_e32 v2, 1.0, v2
	v_add_f32_e32 v72, v79, v68
	v_rcp_f32_e32 v68, v2
	v_mul_f32_e32 v2, 0xbfb8aa3b, v70
	v_exp_f32_e32 v2, v2
	s_nop 0
	v_add_f32_e32 v2, 1.0, v2
	v_rcp_f32_e32 v69, v2
	v_mul_f32_e32 v2, 0xbfb8aa3b, v71
	v_exp_f32_e32 v2, v2
	v_pk_fma_f32 v[192:193], v[52:53], v[68:69], v[192:193]
	v_add_f32_e32 v2, 1.0, v2
	v_rcp_f32_e32 v52, v2
	v_mul_f32_e32 v2, 0xbfb8aa3b, v72
	v_exp_f32_e32 v2, v2
	s_nop 0
	v_add_f32_e32 v2, 1.0, v2
	v_rcp_f32_e32 v53, v2
	s_nop 0
	v_pk_fma_f32 v[194:195], v[54:55], v[52:53], v[194:195]
	v_mov_b32_e32 v52, v130
	v_mov_b32_e32 v53, v131
	global_load_dwordx4 v[72:75], v[80:81], off offset:32
	s_waitcnt vmcnt(1)
	v_lshlrev_b32_e32 v2, 16, v52
	s_waitcnt vmcnt(0)
	v_add_f32_e32 v2, v72, v2
	v_mul_f32_e32 v2, 0xbfb8aa3b, v2
	v_exp_f32_e32 v2, v2
	v_and_b32_e32 v52, 0xffff0000, v52
	v_add_f32_e32 v54, v73, v52
	v_lshlrev_b32_e32 v52, 16, v53
	v_add_f32_e32 v55, v74, v52
	v_and_b32_e32 v52, 0xffff0000, v53
	v_add_f32_e32 v2, 1.0, v2
	v_add_f32_e32 v68, v75, v52
	v_rcp_f32_e32 v52, v2
	v_mul_f32_e32 v2, 0xbfb8aa3b, v54
	v_exp_f32_e32 v2, v2
	s_nop 0
	v_add_f32_e32 v2, 1.0, v2
	v_rcp_f32_e32 v53, v2
	v_mul_f32_e32 v2, 0xbfb8aa3b, v55
	v_exp_f32_e32 v2, v2
	v_pk_fma_f32 v[188:189], v[56:57], v[52:53], v[188:189]
	v_add_f32_e32 v2, 1.0, v2
	v_rcp_f32_e32 v52, v2
	v_mul_f32_e32 v2, 0xbfb8aa3b, v68
	v_exp_f32_e32 v2, v2
	s_nop 0
	v_add_f32_e32 v2, 1.0, v2
	v_rcp_f32_e32 v53, v2
	s_nop 0
	v_pk_fma_f32 v[190:191], v[58:59], v[52:53], v[190:191]
	v_mov_b32_e32 v52, v132
	v_mov_b32_e32 v53, v133
	global_load_dwordx4 v[56:59], v[80:81], off offset:64
	s_waitcnt vmcnt(1)
	v_lshlrev_b32_e32 v2, 16, v52
	s_waitcnt vmcnt(0)
; DI float bflo(uint32_t u) { return __uint_as_float(u << 16); }
; DI float bfhi(uint32_t u) { return __uint_as_float(u & 0xffff0000u); }
; DI float fsigmoid(float x) { return frcp(1.f + fexp2(-LOG2E * x)); }
; DI void phase_branch(const Params& p, int layer, char* smem, int xcd, int loc, int nloc) {
;     ...
;       const float* gb = p.gate_b + ((size_t)layer * 3 + n) * 1024;
; #pragma unroll
;       for (int mi = 0; mi < 2; ++mi) {
;         const int m = m0 + wm * 64 + mi * 32 + r;
; #pragma unroll
;         for (int ni = 0; ni < 2; ++ni)
; #pragma unroll
;           for (int g = 0; g < 4; ++g) {
;             const int d4 = d0 + wn * 64 + ni * 32 + 8 * g + 4 * h;
;             uint2 gu = *(const uint2*)(PROJ + (size_t)m * LDP + O_G + n * 1024 + d4);
;             float4 bb = *(const float4*)(gb + d4);
;             float g0 = bflo(gu.x) + bb.x, g1 = bfhi(gu.x) + bb.y, g2 = bflo(gu.y) + bb.z, g3 = bfhi(gu.y) + bb.w;
;             sum[ni][mi][4 * g] += acc[ni][mi][4 * g] * fsigmoid(g0);
;             sum[ni][mi][4 * g + 1] += acc[ni][mi][4 * g + 1] * fsigmoid(g1);
;             sum[ni][mi][4 * g + 2] += acc[ni][mi][4 * g + 2] * fsigmoid(g2);
;             sum[ni][mi][4 * g + 3] += acc[ni][mi][4 * g + 3] * fsigmoid(g3);
;           }
;       }
	v_add_f32_e32 v2, v56, v2
	v_mul_f32_e32 v2, 0xbfb8aa3b, v2
	v_exp_f32_e32 v2, v2
	v_and_b32_e32 v52, 0xffff0000, v52
	v_add_f32_e32 v54, v57, v52
	v_lshlrev_b32_e32 v52, 16, v53
	v_add_f32_e32 v55, v58, v52
	v_and_b32_e32 v52, 0xffff0000, v53
	v_add_f32_e32 v2, 1.0, v2
	v_add_f32_e32 v68, v59, v52
	v_rcp_f32_e32 v52, v2
	v_mul_f32_e32 v2, 0xbfb8aa3b, v54
	v_exp_f32_e32 v2, v2
	s_nop 0
	v_add_f32_e32 v2, 1.0, v2
	v_rcp_f32_e32 v53, v2
	v_mul_f32_e32 v2, 0xbfb8aa3b, v55
	v_exp_f32_e32 v2, v2
	v_pk_fma_f32 v[184:185], v[60:61], v[52:53], v[184:185]
	v_add_f32_e32 v2, 1.0, v2
	v_rcp_f32_e32 v52, v2
	v_mul_f32_e32 v2, 0xbfb8aa3b, v68
	v_exp_f32_e32 v2, v2
	s_nop 0
	v_add_f32_e32 v2, 1.0, v2
	v_rcp_f32_e32 v53, v2
	s_nop 0
	v_pk_fma_f32 v[186:187], v[62:63], v[52:53], v[186:187]
	v_mov_b32_e32 v52, v196
	v_mov_b32_e32 v53, v197
	global_load_dwordx4 v[68:71], v[80:81], off offset:96
	s_waitcnt vmcnt(1)
	v_lshlrev_b32_e32 v2, 16, v52
	s_waitcnt vmcnt(0)
	v_add_f32_e32 v2, v68, v2
	v_mul_f32_e32 v2, 0xbfb8aa3b, v2
	v_exp_f32_e32 v2, v2
	v_and_b32_e32 v52, 0xffff0000, v52
	v_add_f32_e32 v54, v69, v52
	v_lshlrev_b32_e32 v52, 16, v53
	v_add_f32_e32 v55, v70, v52
	v_and_b32_e32 v52, 0xffff0000, v53
	v_add_f32_e32 v2, 1.0, v2
	v_add_f32_e32 v60, v71, v52
	v_rcp_f32_e32 v52, v2
	v_mul_f32_e32 v2, 0xbfb8aa3b, v54
	v_exp_f32_e32 v2, v2
	s_nop 0
	v_add_f32_e32 v2, 1.0, v2
	v_rcp_f32_e32 v53, v2
	v_mul_f32_e32 v2, 0xbfb8aa3b, v55
	v_exp_f32_e32 v2, v2
	v_pk_fma_f32 v[182:183], v[64:65], v[52:53], v[182:183]
	v_add_f32_e32 v2, 1.0, v2
	v_rcp_f32_e32 v52, v2
	v_mul_f32_e32 v2, 0xbfb8aa3b, v60
	v_exp_f32_e32 v2, v2
	s_nop 0
	v_add_f32_e32 v2, 1.0, v2
	v_rcp_f32_e32 v53, v2
	s_nop 0
	v_pk_fma_f32 v[180:181], v[66:67], v[52:53], v[180:181]
	v_mov_b32_e32 v60, v198
	v_mov_b32_e32 v61, v199
	global_load_dwordx4 v[52:55], v[80:81], off offset:128
	s_waitcnt vmcnt(1)
	v_lshlrev_b32_e32 v2, 16, v60
	s_waitcnt vmcnt(0)
	v_add_f32_e32 v2, v52, v2
	v_mul_f32_e32 v2, 0xbfb8aa3b, v2
	v_exp_f32_e32 v2, v2
	v_and_b32_e32 v60, 0xffff0000, v60
	v_add_f32_e32 v62, v53, v60
	v_lshlrev_b32_e32 v60, 16, v61
	v_add_f32_e32 v63, v54, v60
	v_and_b32_e32 v60, 0xffff0000, v61
	v_add_f32_e32 v2, 1.0, v2
	v_add_f32_e32 v64, v55, v60
	v_rcp_f32_e32 v60, v2
	v_mul_f32_e32 v2, 0xbfb8aa3b, v62
	v_exp_f32_e32 v2, v2
	s_nop 0
	v_add_f32_e32 v2, 1.0, v2
	v_rcp_f32_e32 v61, v2
	v_mul_f32_e32 v2, 0xbfb8aa3b, v63
	v_exp_f32_e32 v2, v2
	v_pk_fma_f32 v[176:177], v[36:37], v[60:61], v[176:177]
	v_add_f32_e32 v2, 1.0, v2
	v_rcp_f32_e32 v36, v2
	v_mul_f32_e32 v2, 0xbfb8aa3b, v64
	v_exp_f32_e32 v2, v2
	s_nop 0
	v_add_f32_e32 v2, 1.0, v2
	v_rcp_f32_e32 v37, v2
	s_nop 0
	v_pk_fma_f32 v[178:179], v[38:39], v[36:37], v[178:179]
	v_mov_b32_e32 v36, v200
	v_mov_b32_e32 v37, v201
	global_load_dwordx4 v[60:63], v[80:81], off offset:160
	s_waitcnt vmcnt(1)
	v_lshlrev_b32_e32 v2, 16, v36
	s_waitcnt vmcnt(0)
	v_add_f32_e32 v2, v60, v2
	v_mul_f32_e32 v2, 0xbfb8aa3b, v2
	v_exp_f32_e32 v2, v2
	v_and_b32_e32 v36, 0xffff0000, v36
	v_add_f32_e32 v38, v61, v36
	v_lshlrev_b32_e32 v36, 16, v37
	v_add_f32_e32 v39, v62, v36
	v_and_b32_e32 v36, 0xffff0000, v37
	v_add_f32_e32 v2, 1.0, v2
	v_add_f32_e32 v64, v63, v36
	v_rcp_f32_e32 v36, v2
	v_mul_f32_e32 v2, 0xbfb8aa3b, v38
	v_exp_f32_e32 v2, v2
	s_nop 0
	v_add_f32_e32 v2, 1.0, v2
	v_rcp_f32_e32 v37, v2
	v_mul_f32_e32 v2, 0xbfb8aa3b, v39
	v_exp_f32_e32 v2, v2
	v_pk_fma_f32 v[172:173], v[40:41], v[36:37], v[172:173]
	v_add_f32_e32 v2, 1.0, v2
	v_rcp_f32_e32 v36, v2
	v_mul_f32_e32 v2, 0xbfb8aa3b, v64
	v_exp_f32_e32 v2, v2
	s_nop 0
	v_add_f32_e32 v2, 1.0, v2
	v_rcp_f32_e32 v37, v2
	s_nop 0
	v_pk_fma_f32 v[174:175], v[42:43], v[36:37], v[174:175]
	v_mov_b32_e32 v36, v230
	v_mov_b32_e32 v37, v231
	global_load_dwordx4 v[40:43], v[80:81], off offset:192
	s_waitcnt vmcnt(1)
	v_lshlrev_b32_e32 v2, 16, v36
	s_waitcnt vmcnt(0)
	v_add_f32_e32 v2, v40, v2
	v_mul_f32_e32 v2, 0xbfb8aa3b, v2
	v_exp_f32_e32 v2, v2
	v_and_b32_e32 v36, 0xffff0000, v36
	v_add_f32_e32 v38, v41, v36
	v_lshlrev_b32_e32 v36, 16, v37
	v_add_f32_e32 v39, v42, v36
	v_and_b32_e32 v36, 0xffff0000, v37
	v_add_f32_e32 v2, 1.0, v2
	v_add_f32_e32 v64, v43, v36
	v_rcp_f32_e32 v36, v2
	v_mul_f32_e32 v2, 0xbfb8aa3b, v38
	v_exp_f32_e32 v2, v2
	s_nop 0
	v_add_f32_e32 v2, 1.0, v2
	v_rcp_f32_e32 v37, v2
	v_mul_f32_e32 v2, 0xbfb8aa3b, v39
	v_exp_f32_e32 v2, v2
	v_pk_fma_f32 v[168:169], v[44:45], v[36:37], v[168:169]
	v_add_f32_e32 v2, 1.0, v2
	v_rcp_f32_e32 v36, v2
	v_mul_f32_e32 v2, 0xbfb8aa3b, v64
	v_exp_f32_e32 v2, v2
	s_nop 0
	v_add_f32_e32 v2, 1.0, v2
	v_rcp_f32_e32 v37, v2
	s_nop 0
	v_pk_fma_f32 v[170:171], v[46:47], v[36:37], v[170:171]
	v_mov_b32_e32 v44, v232
	v_mov_b32_e32 v45, v233
	global_load_dwordx4 v[36:39], v[80:81], off offset:224
	s_waitcnt vmcnt(1)
	v_lshlrev_b32_e32 v2, 16, v44
	s_waitcnt vmcnt(0)
	v_add_f32_e32 v2, v36, v2
	v_mul_f32_e32 v2, 0xbfb8aa3b, v2
	v_exp_f32_e32 v2, v2
	v_and_b32_e32 v44, 0xffff0000, v44
	v_add_f32_e32 v46, v37, v44
	v_lshlrev_b32_e32 v44, 16, v45
	v_add_f32_e32 v47, v38, v44
	v_and_b32_e32 v44, 0xffff0000, v45
	v_add_f32_e32 v2, 1.0, v2
	v_add_f32_e32 v64, v39, v44
	v_rcp_f32_e32 v44, v2
	v_mul_f32_e32 v2, 0xbfb8aa3b, v46
	v_exp_f32_e32 v2, v2
	s_nop 0
	v_add_f32_e32 v2, 1.0, v2
	v_rcp_f32_e32 v45, v2
	v_mul_f32_e32 v2, 0xbfb8aa3b, v47
	v_exp_f32_e32 v2, v2
	v_pk_fma_f32 v[166:167], v[48:49], v[44:45], v[166:167]
	v_add_f32_e32 v2, 1.0, v2
	v_rcp_f32_e32 v44, v2
	v_mul_f32_e32 v2, 0xbfb8aa3b, v64
	v_exp_f32_e32 v2, v2
	s_nop 0
	v_add_f32_e32 v2, 1.0, v2
	v_rcp_f32_e32 v45, v2
	s_nop 0
	v_pk_fma_f32 v[126:127], v[50:51], v[44:45], v[126:127]
	v_lshl_add_u64 v[44:45], v[150:151], 0, s[12:13]
	v_mov_b32_e32 v46, v234
	v_mov_b32_e32 v47, v235
	s_waitcnt vmcnt(0)
; DI float bflo(uint32_t u) { return __uint_as_float(u << 16); }
; DI float bfhi(uint32_t u) { return __uint_as_float(u & 0xffff0000u); }
; DI float fsigmoid(float x) { return frcp(1.f + fexp2(-LOG2E * x)); }
; DI void phase_branch(const Params& p, int layer, char* smem, int xcd, int loc, int nloc) {
;     ...
;       const float* gb = p.gate_b + ((size_t)layer * 3 + n) * 1024;
; #pragma unroll
;       for (int mi = 0; mi < 2; ++mi) {
;         const int m = m0 + wm * 64 + mi * 32 + r;
; #pragma unroll
;         for (int ni = 0; ni < 2; ++ni)
; #pragma unroll
;           for (int g = 0; g < 4; ++g) {
;             const int d4 = d0 + wn * 64 + ni * 32 + 8 * g + 4 * h;
;             uint2 gu = *(const uint2*)(PROJ + (size_t)m * LDP + O_G + n * 1024 + d4);
;             float4 bb = *(const float4*)(gb + d4);
;             float g0 = bflo(gu.x) + bb.x, g1 = bfhi(gu.x) + bb.y, g2 = bflo(gu.y) + bb.z, g3 = bfhi(gu.y) + bb.w;
;             sum[ni][mi][4 * g] += acc[ni][mi][4 * g] * fsigmoid(g0);
;             sum[ni][mi][4 * g + 1] += acc[ni][mi][4 * g + 1] * fsigmoid(g1);
;             sum[ni][mi][4 * g + 2] += acc[ni][mi][4 * g + 2] * fsigmoid(g2);
;             sum[ni][mi][4 * g + 3] += acc[ni][mi][4 * g + 3] * fsigmoid(g3);
;           }
;       }
	v_lshlrev_b32_e32 v2, 16, v46
	v_add_f32_e32 v2, v76, v2
	v_mul_f32_e32 v2, 0xbfb8aa3b, v2
	v_exp_f32_e32 v2, v2
	v_and_b32_e32 v46, 0xffff0000, v46
	v_add_f32_e32 v48, v77, v46
	v_lshlrev_b32_e32 v46, 16, v47
	v_add_f32_e32 v49, v78, v46
	v_and_b32_e32 v46, 0xffff0000, v47
	v_add_f32_e32 v2, 1.0, v2
	v_add_f32_e32 v50, v79, v46
	v_rcp_f32_e32 v46, v2
	v_mul_f32_e32 v2, 0xbfb8aa3b, v48
	v_exp_f32_e32 v2, v2
	s_nop 0
	v_add_f32_e32 v2, 1.0, v2
	v_rcp_f32_e32 v47, v2
	v_mul_f32_e32 v2, 0xbfb8aa3b, v49
	v_exp_f32_e32 v2, v2
	v_pk_fma_f32 v[162:163], v[20:21], v[46:47], v[162:163]
	v_add_f32_e32 v2, 1.0, v2
	v_rcp_f32_e32 v20, v2
	v_mul_f32_e32 v2, 0xbfb8aa3b, v50
	v_exp_f32_e32 v2, v2
	s_nop 0
	v_add_f32_e32 v2, 1.0, v2
	v_rcp_f32_e32 v21, v2
	s_nop 0
	v_pk_fma_f32 v[164:165], v[22:23], v[20:21], v[164:165]
	v_mov_b32_e32 v20, v236
	v_mov_b32_e32 v21, v237
	s_waitcnt vmcnt(0)
	v_lshlrev_b32_e32 v2, 16, v20
	v_add_f32_e32 v2, v72, v2
	v_mul_f32_e32 v2, 0xbfb8aa3b, v2
	v_exp_f32_e32 v2, v2
	v_and_b32_e32 v20, 0xffff0000, v20
	v_add_f32_e32 v22, v73, v20
	v_lshlrev_b32_e32 v20, 16, v21
	v_add_f32_e32 v23, v74, v20
	v_and_b32_e32 v20, 0xffff0000, v21
	v_add_f32_e32 v2, 1.0, v2
	v_add_f32_e32 v46, v75, v20
	v_rcp_f32_e32 v20, v2
	v_mul_f32_e32 v2, 0xbfb8aa3b, v22
	v_exp_f32_e32 v2, v2
	s_nop 0
	v_add_f32_e32 v2, 1.0, v2
	v_rcp_f32_e32 v21, v2
	v_mul_f32_e32 v2, 0xbfb8aa3b, v23
	v_exp_f32_e32 v2, v2
	v_pk_fma_f32 v[158:159], v[24:25], v[20:21], v[158:159]
	v_add_f32_e32 v2, 1.0, v2
	v_rcp_f32_e32 v20, v2
	v_mul_f32_e32 v2, 0xbfb8aa3b, v46
	v_exp_f32_e32 v2, v2
	s_nop 0
	v_add_f32_e32 v2, 1.0, v2
	v_rcp_f32_e32 v21, v2
	s_nop 0
	v_pk_fma_f32 v[160:161], v[26:27], v[20:21], v[160:161]
	v_mov_b32_e32 v20, v238
	v_mov_b32_e32 v21, v239
	s_waitcnt vmcnt(0)
	v_lshlrev_b32_e32 v2, 16, v20
	v_add_f32_e32 v2, v56, v2
	v_mul_f32_e32 v2, 0xbfb8aa3b, v2
	v_exp_f32_e32 v2, v2
	v_and_b32_e32 v20, 0xffff0000, v20
	v_add_f32_e32 v22, v57, v20
	v_lshlrev_b32_e32 v20, 16, v21
	v_add_f32_e32 v23, v58, v20
	v_and_b32_e32 v20, 0xffff0000, v21
	v_add_f32_e32 v2, 1.0, v2
	v_add_f32_e32 v24, v59, v20
	v_rcp_f32_e32 v20, v2
	v_mul_f32_e32 v2, 0xbfb8aa3b, v22
	v_exp_f32_e32 v2, v2
	s_nop 0
	v_add_f32_e32 v2, 1.0, v2
	v_rcp_f32_e32 v21, v2
	v_mul_f32_e32 v2, 0xbfb8aa3b, v23
	v_exp_f32_e32 v2, v2
	v_pk_fma_f32 v[154:155], v[28:29], v[20:21], v[154:155]
	v_add_f32_e32 v2, 1.0, v2
	v_rcp_f32_e32 v20, v2
	v_mul_f32_e32 v2, 0xbfb8aa3b, v24
	v_exp_f32_e32 v2, v2
	s_nop 0
	v_add_f32_e32 v2, 1.0, v2
	v_rcp_f32_e32 v21, v2
	s_nop 0
	v_pk_fma_f32 v[156:157], v[30:31], v[20:21], v[156:157]
	v_mov_b32_e32 v20, v240
	v_mov_b32_e32 v21, v241
	s_waitcnt vmcnt(0)
	v_lshlrev_b32_e32 v2, 16, v20
	v_add_f32_e32 v2, v68, v2
	v_mul_f32_e32 v2, 0xbfb8aa3b, v2
	v_exp_f32_e32 v2, v2
	v_and_b32_e32 v20, 0xffff0000, v20
	v_add_f32_e32 v22, v69, v20
	v_lshlrev_b32_e32 v20, 16, v21
	v_add_f32_e32 v23, v70, v20
	v_and_b32_e32 v20, 0xffff0000, v21
	v_add_f32_e32 v2, 1.0, v2
	v_add_f32_e32 v24, v71, v20
	v_rcp_f32_e32 v20, v2
	v_mul_f32_e32 v2, 0xbfb8aa3b, v22
	v_exp_f32_e32 v2, v2
	s_nop 0
	v_add_f32_e32 v2, 1.0, v2
	v_rcp_f32_e32 v21, v2
	v_mul_f32_e32 v2, 0xbfb8aa3b, v23
	v_exp_f32_e32 v2, v2
	v_pk_fma_f32 v[152:153], v[32:33], v[20:21], v[152:153]
	v_add_f32_e32 v2, 1.0, v2
	v_rcp_f32_e32 v20, v2
	v_mul_f32_e32 v2, 0xbfb8aa3b, v24
	v_exp_f32_e32 v2, v2
	s_nop 0
	v_add_f32_e32 v2, 1.0, v2
	v_rcp_f32_e32 v21, v2
	s_nop 0
	v_pk_fma_f32 v[120:121], v[34:35], v[20:21], v[120:121]
	v_mov_b32_e32 v20, v242
	v_mov_b32_e32 v21, v243
	s_waitcnt vmcnt(0)
	v_lshlrev_b32_e32 v2, 16, v20
	v_add_f32_e32 v2, v52, v2
	v_mul_f32_e32 v2, 0xbfb8aa3b, v2
	v_exp_f32_e32 v2, v2
	v_and_b32_e32 v20, 0xffff0000, v20
	v_add_f32_e32 v22, v53, v20
	v_lshlrev_b32_e32 v20, 16, v21
	v_add_f32_e32 v23, v54, v20
	v_and_b32_e32 v20, 0xffff0000, v21
	v_add_f32_e32 v2, 1.0, v2
	v_add_f32_e32 v24, v55, v20
	v_rcp_f32_e32 v20, v2
	v_mul_f32_e32 v2, 0xbfb8aa3b, v22
	v_exp_f32_e32 v2, v2
	s_nop 0
	v_add_f32_e32 v2, 1.0, v2
	v_rcp_f32_e32 v21, v2
	v_mul_f32_e32 v2, 0xbfb8aa3b, v23
	v_exp_f32_e32 v2, v2
	v_pk_fma_f32 v[114:115], v[4:5], v[20:21], v[114:115]
	v_add_f32_e32 v2, 1.0, v2
	v_rcp_f32_e32 v4, v2
	v_mul_f32_e32 v2, 0xbfb8aa3b, v24
	v_exp_f32_e32 v2, v2
	s_nop 0
	v_add_f32_e32 v2, 1.0, v2
	v_rcp_f32_e32 v5, v2
	s_nop 0
	v_pk_fma_f32 v[116:117], v[6:7], v[4:5], v[116:117]
	v_mov_b32_e32 v4, v244
	v_mov_b32_e32 v5, v245
	s_waitcnt vmcnt(0)
	v_lshlrev_b32_e32 v2, 16, v4
	v_add_f32_e32 v2, v60, v2
	v_mul_f32_e32 v2, 0xbfb8aa3b, v2
	v_exp_f32_e32 v2, v2
	v_and_b32_e32 v4, 0xffff0000, v4
	v_add_f32_e32 v6, v61, v4
	v_lshlrev_b32_e32 v4, 16, v5
	v_add_f32_e32 v7, v62, v4
	v_and_b32_e32 v4, 0xffff0000, v5
	v_add_f32_e32 v2, 1.0, v2
	v_add_f32_e32 v20, v63, v4
	v_rcp_f32_e32 v4, v2
	v_mul_f32_e32 v2, 0xbfb8aa3b, v6
	v_exp_f32_e32 v2, v2
	s_nop 0
	v_add_f32_e32 v2, 1.0, v2
	v_rcp_f32_e32 v5, v2
	v_mul_f32_e32 v2, 0xbfb8aa3b, v7
	v_exp_f32_e32 v2, v2
	v_pk_fma_f32 v[110:111], v[8:9], v[4:5], v[110:111]
	v_add_f32_e32 v2, 1.0, v2
	v_rcp_f32_e32 v4, v2
	v_mul_f32_e32 v2, 0xbfb8aa3b, v20
	v_exp_f32_e32 v2, v2
	s_nop 0
	v_add_f32_e32 v2, 1.0, v2
	v_rcp_f32_e32 v5, v2
	s_nop 0
	v_pk_fma_f32 v[112:113], v[10:11], v[4:5], v[112:113]
	v_mov_b32_e32 v4, v246
	v_mov_b32_e32 v5, v247
	s_waitcnt vmcnt(0)
	v_lshlrev_b32_e32 v2, 16, v4
	v_add_f32_e32 v2, v40, v2
	v_mul_f32_e32 v2, 0xbfb8aa3b, v2
	v_exp_f32_e32 v2, v2
	v_and_b32_e32 v4, 0xffff0000, v4
	v_add_f32_e32 v6, v41, v4
	v_lshlrev_b32_e32 v4, 16, v5
	v_add_f32_e32 v7, v42, v4
	v_and_b32_e32 v4, 0xffff0000, v5
	v_add_f32_e32 v2, 1.0, v2
	v_add_f32_e32 v8, v43, v4
	v_rcp_f32_e32 v4, v2
	v_mul_f32_e32 v2, 0xbfb8aa3b, v6
	v_exp_f32_e32 v2, v2
	s_nop 0
	v_add_f32_e32 v2, 1.0, v2
	v_rcp_f32_e32 v5, v2
	v_mul_f32_e32 v2, 0xbfb8aa3b, v7
	v_exp_f32_e32 v2, v2
	v_pk_fma_f32 v[106:107], v[12:13], v[4:5], v[106:107]
	v_add_f32_e32 v2, 1.0, v2
	v_rcp_f32_e32 v4, v2
	v_mul_f32_e32 v2, 0xbfb8aa3b, v8
	v_exp_f32_e32 v2, v2
	s_nop 0
	v_add_f32_e32 v2, 1.0, v2
	v_rcp_f32_e32 v5, v2
	s_nop 0
	v_pk_fma_f32 v[108:109], v[14:15], v[4:5], v[108:109]
	v_mov_b32_e32 v4, v248
	v_mov_b32_e32 v5, v249
	s_waitcnt vmcnt(0)
	v_lshlrev_b32_e32 v2, 16, v4
	v_add_f32_e32 v2, v36, v2
	v_mul_f32_e32 v2, 0xbfb8aa3b, v2
	v_exp_f32_e32 v2, v2
	v_and_b32_e32 v4, 0xffff0000, v4
	v_add_f32_e32 v6, v37, v4
	v_lshlrev_b32_e32 v4, 16, v5
	v_add_f32_e32 v7, v38, v4
	v_and_b32_e32 v4, 0xffff0000, v5
	v_add_f32_e32 v2, 1.0, v2
	v_add_f32_e32 v8, v39, v4
	v_rcp_f32_e32 v4, v2
	v_mul_f32_e32 v2, 0xbfb8aa3b, v6
	v_exp_f32_e32 v2, v2
	s_nop 0
	v_add_f32_e32 v2, 1.0, v2
	v_rcp_f32_e32 v5, v2
	v_mul_f32_e32 v2, 0xbfb8aa3b, v7
	v_exp_f32_e32 v2, v2
	v_pk_fma_f32 v[104:105], v[16:17], v[4:5], v[104:105]
	v_add_f32_e32 v2, 1.0, v2
	v_rcp_f32_e32 v4, v2
	v_mul_f32_e32 v2, 0xbfb8aa3b, v8
	v_exp_f32_e32 v2, v2
	s_nop 0
	v_add_f32_e32 v2, 1.0, v2
	v_rcp_f32_e32 v5, v2
	s_nop 0
	v_pk_fma_f32 v[100:101], v[18:19], v[4:5], v[100:101]
	s_cbranch_scc0 .LBB0_18
; DI uint32_t pack2(float a, float b) { f2_t v = {a, b}; bf2_t r = __builtin_convertvector(v, bf2_t); return __builtin_bit_cast(uint32_t, r); }
; DI void phase_branch(const Params& p, int layer, char* smem, int xcd, int loc, int nloc) {
;     ...
;   for (int i = loc;; i += nloc) {
;     int mt, nt;
;     if (!tile_order<8>(i, xcd, mt, nt)) break;
;     ...
; #pragma unroll
;     for (int mi = 0; mi < 2; ++mi) {
;       const int m = m0 + wm * 64 + mi * 32 + r;
; #pragma unroll
;       for (int ni = 0; ni < 2; ++ni)
; #pragma unroll
;         for (int g = 0; g < 4; ++g) {
;           const int d4 = d0 + wn * 64 + ni * 32 + 8 * g + 4 * h;
;           *(uint2*)(MG + (size_t)m * LDX + d4) = make_uint2(pack2(sum[ni][mi][4 * g], sum[ni][mi][4 * g + 1]), pack2(sum[ni][mi][4 * g + 2], sum[ni][mi][4 * g + 3]));
;         }
;     }
;   }
	v_mov_b64_e32 v[4:5], s[20:21]
	v_mad_i64_i32 v[6:7], s[6:7], v118, s24, v[4:5]
	v_cvt_pk_bf16_f32 v8, v192, v193
	v_cvt_pk_bf16_f32 v9, v194, v195
	v_lshl_add_u64 v[6:7], v[6:7], 0, v[102:103]
	global_store_dwordx2 v[6:7], v[8:9], off
	v_cvt_pk_bf16_f32 v8, v188, v189
	v_cvt_pk_bf16_f32 v9, v190, v191
	global_store_dwordx2 v[6:7], v[8:9], off offset:16
	v_cvt_pk_bf16_f32 v8, v184, v185
	v_cvt_pk_bf16_f32 v9, v186, v187
	global_store_dwordx2 v[6:7], v[8:9], off offset:32
	v_cvt_pk_bf16_f32 v8, v182, v183
	v_cvt_pk_bf16_f32 v9, v180, v181
	global_store_dwordx2 v[6:7], v[8:9], off offset:48
	v_cvt_pk_bf16_f32 v8, v176, v177
	v_cvt_pk_bf16_f32 v9, v178, v179
	global_store_dwordx2 v[6:7], v[8:9], off offset:64
	v_cvt_pk_bf16_f32 v8, v172, v173
	v_cvt_pk_bf16_f32 v9, v174, v175
	global_store_dwordx2 v[6:7], v[8:9], off offset:80
	v_cvt_pk_bf16_f32 v8, v168, v169
	v_cvt_pk_bf16_f32 v9, v170, v171
	global_store_dwordx2 v[6:7], v[8:9], off offset:96
	v_cvt_pk_bf16_f32 v8, v166, v167
	v_cvt_pk_bf16_f32 v9, v126, v127
	v_mad_i64_i32 v[4:5], s[6:7], v0, s24, v[4:5]
	global_store_dwordx2 v[6:7], v[8:9], off offset:112
	v_cvt_pk_bf16_f32 v6, v162, v163
	v_cvt_pk_bf16_f32 v7, v164, v165
	v_lshl_add_u64 v[4:5], v[4:5], 0, v[102:103]
	global_store_dwordx2 v[4:5], v[6:7], off
	v_cvt_pk_bf16_f32 v6, v158, v159
	v_cvt_pk_bf16_f32 v7, v160, v161
	global_store_dwordx2 v[4:5], v[6:7], off offset:16
	v_cvt_pk_bf16_f32 v6, v154, v155
	v_cvt_pk_bf16_f32 v7, v156, v157
	global_store_dwordx2 v[4:5], v[6:7], off offset:32
	v_cvt_pk_bf16_f32 v6, v152, v153
	v_cvt_pk_bf16_f32 v7, v120, v121
	global_store_dwordx2 v[4:5], v[6:7], off offset:48
	v_cvt_pk_bf16_f32 v6, v114, v115
	v_cvt_pk_bf16_f32 v7, v116, v117
	global_store_dwordx2 v[4:5], v[6:7], off offset:64
	v_cvt_pk_bf16_f32 v6, v110, v111
	v_cvt_pk_bf16_f32 v7, v112, v113
	global_store_dwordx2 v[4:5], v[6:7], off offset:80
	v_cvt_pk_bf16_f32 v6, v106, v107
	v_cvt_pk_bf16_f32 v7, v108, v109
	s_add_i32 s31, s31, s33
	s_add_i32 s30, s30, s33
	global_store_dwordx2 v[4:5], v[6:7], off offset:96
	v_cvt_pk_bf16_f32 v6, v104, v105
	v_cvt_pk_bf16_f32 v7, v100, v101
	s_cmpk_gt_i32 s31, 0x7f
	global_store_dwordx2 v[4:5], v[6:7], off offset:112
	s_cbranch_scc0 .LBB0_17

; #define MFMA32(a, b, c) __builtin_amdgcn_mfma_f32_32x32x16_bf16((a), (b), (c), 0, 0, 0)
; #define G_LOAD(KOFF) do { rw0 = *(const uint4*)(gw + (KOFF)); rw1 = *(const uint4*)(gw1 + (KOFF)); rw2 = *(const uint4*)(gw2 + (KOFF)); rw3 = *(const uint4*)(gw3 + (KOFF)); \
;                           rx0 = *(const uint4*)(gx + (KOFF)); rx1 = *(const uint4*)(gx1 + (KOFF)); rx2 = *(const uint4*)(gx2 + (KOFF)); rx3 = *(const uint4*)(gx3 + (KOFF)); } while (0)
; DI void gemm128(const u16* __restrict__ W, int ldw, const u16* __restrict__ X, int ldx, int K, f32x16 (&acc)[2][2], char* smem) {
;     ...
;   for (int kt = 0; kt < nk; ++kt) {
;     const int buf = kt & 1;
; #pragma unroll
;     for (int ks = 0; ks < 4; ++ks) {
;       bf16x8 a0 = *(const bf16x8*)&sw[buf][wn * 64 + r][ks * 16 + h * 8];
;       bf16x8 a1 = *(const bf16x8*)&sw[buf][wn * 64 + 32 + r][ks * 16 + h * 8];
;       bf16x8 b0 = *(const bf16x8*)&sx[buf][wm * 64 + r][ks * 16 + h * 8];
;       bf16x8 b1 = *(const bf16x8*)&sx[buf][wm * 64 + 32 + r][ks * 16 + h * 8];
;       acc[0][0] = MFMA32(a0, b0, acc[0][0]);
;       acc[0][1] = MFMA32(a0, b1, acc[0][1]);
;       acc[1][0] = MFMA32(a1, b0, acc[1][0]);
;       acc[1][1] = MFMA32(a1, b1, acc[1][1]);
;     }
;     if (kt + 1 < nk) G_STORE(buf ^ 1);
;     if (kt + 2 < nk) G_LOAD((kt + 2) * 64);
;     __syncthreads();
;   }
.LBB0_1401:
	s_and_b32 s0, s36, 1
	s_mul_i32 s1, s0, 0x4800
	v_add_u32_e32 v2, s1, v106
	ds_read_b128 v[108:111], v2 offset:4608
	v_add_u32_e32 v107, s1, v1
	ds_read_b128 v[112:115], v107 offset:41472
	ds_read_b128 v[116:119], v2
	ds_read_b128 v[120:123], v2 offset:32
	ds_read_b128 v[124:127], v107 offset:36864
	ds_read_b128 v[130:133], v107 offset:36896
	s_waitcnt lgkmcnt(3)
	v_mfma_f32_32x32x16_bf16 v[20:35], v[116:119], v[112:115], v[20:35]
	s_xor_b32 s0, s0, 1
	s_mulk_i32 s0, 0x4800
	s_add_i32 s36, s36, 1
	s_waitcnt lgkmcnt(1)
	v_mfma_f32_32x32x16_bf16 v[52:67], v[116:119], v[124:127], v[52:67]
	v_mfma_f32_32x32x16_bf16 v[36:51], v[108:111], v[124:127], v[36:51]
	v_mfma_f32_32x32x16_bf16 v[4:19], v[108:111], v[112:115], v[4:19]
	ds_read_b128 v[108:111], v2 offset:4640
	ds_read_b128 v[112:115], v107 offset:41504
	s_waitcnt lgkmcnt(2)
	v_mfma_f32_32x32x16_bf16 v[52:67], v[120:123], v[130:133], v[52:67]
	s_waitcnt lgkmcnt(0)
	v_mfma_f32_32x32x16_bf16 v[20:35], v[120:123], v[112:115], v[20:35]
	v_mfma_f32_32x32x16_bf16 v[36:51], v[108:111], v[130:133], v[36:51]
	v_mfma_f32_32x32x16_bf16 v[4:19], v[108:111], v[112:115], v[4:19]
	ds_read_b128 v[108:111], v2 offset:64
	ds_read_b128 v[112:115], v2 offset:4672
	ds_read_b128 v[116:119], v107 offset:36928
	ds_read_b128 v[120:123], v107 offset:41536
	s_waitcnt lgkmcnt(1)
	v_mfma_f32_32x32x16_bf16 v[52:67], v[108:111], v[116:119], v[52:67]
	s_waitcnt lgkmcnt(0)
	v_mfma_f32_32x32x16_bf16 v[20:35], v[108:111], v[120:123], v[20:35]
	v_mfma_f32_32x32x16_bf16 v[36:51], v[112:115], v[116:119], v[36:51]
	v_mfma_f32_32x32x16_bf16 v[4:19], v[112:115], v[120:123], v[4:19]
	ds_read_b128 v[108:111], v2 offset:96
	ds_read_b128 v[112:115], v2 offset:4704
	ds_read_b128 v[116:119], v107 offset:36960
	ds_read_b128 v[120:123], v107 offset:41568
	v_add_u32_e32 v2, s0, v0
	s_waitcnt vmcnt(7)
	ds_write_b128 v2, v[68:71]
	s_waitcnt vmcnt(6)
	ds_write_b128 v2, v[72:75] offset:4608
	s_waitcnt vmcnt(5)
	ds_write_b128 v2, v[76:79] offset:9216
	s_waitcnt vmcnt(4)
	ds_write_b128 v2, v[80:83] offset:13824
	s_waitcnt vmcnt(3)
	ds_write_b128 v2, v[84:87] offset:36864
	s_waitcnt vmcnt(2)
	ds_write_b128 v2, v[88:91] offset:41472
	s_waitcnt vmcnt(1)
	ds_write_b128 v2, v[92:95] offset:46080
	s_waitcnt vmcnt(0)
	ds_write_b128 v2, v[96:99] offset:50688
	v_lshl_add_u64 v[80:81], v[102:103], 0, s[12:13]
	s_mov_b32 s0, 0x13ac000
	v_add_co_u32_e64 v68, s[0:1], s0, v80
	v_lshl_add_u64 v[96:97], v[100:101], 0, s[12:13]
	s_nop 0
	v_addc_co_u32_e64 v69, s[0:1], 0, v81, s[0:1]
	s_mov_b32 s0, 0x13bd000
	s_nop 0
	v_add_co_u32_e64 v72, s[0:1], s0, v80
	global_load_dwordx4 v[68:71], v[68:69], off offset:256
	s_nop 0
	v_addc_co_u32_e64 v73, s[0:1], 0, v81, s[0:1]
	s_mov_b32 s0, 0x13ce000
	s_nop 0
	v_add_co_u32_e64 v76, s[0:1], s0, v80
	global_load_dwordx4 v[72:75], v[72:73], off offset:256
	s_nop 0
	v_addc_co_u32_e64 v77, s[0:1], 0, v81, s[0:1]
	s_mov_b32 s0, 0x13df000
	s_nop 0
	v_add_co_u32_e64 v80, s[0:1], s0, v80
	global_load_dwordx4 v[76:79], v[76:77], off offset:256
	s_nop 0
	v_addc_co_u32_e64 v81, s[0:1], 0, v81, s[0:1]
	s_mov_b32 s0, 0x10a98000
	s_nop 0
	v_add_co_u32_e64 v84, s[0:1], s0, v96
	global_load_dwordx4 v[80:83], v[80:81], off offset:256
	s_nop 0
	v_addc_co_u32_e64 v85, s[0:1], 0, v97, s[0:1]
	s_mov_b32 s0, 0x10aa9000
	s_nop 0
	v_add_co_u32_e64 v88, s[0:1], s0, v96
	global_load_dwordx4 v[84:87], v[84:85], off offset:256
	s_nop 0
	v_addc_co_u32_e64 v89, s[0:1], 0, v97, s[0:1]
	s_mov_b32 s0, 0x10aba000
	s_nop 0
	v_add_co_u32_e64 v92, s[0:1], s0, v96
	global_load_dwordx4 v[88:91], v[88:89], off offset:256
	s_nop 0
	v_addc_co_u32_e64 v93, s[0:1], 0, v97, s[0:1]
	s_mov_b32 s0, 0x10acb000
	s_nop 0
	v_add_co_u32_e64 v96, s[0:1], s0, v96
	global_load_dwordx4 v[92:95], v[92:93], off offset:256
	s_nop 0
	v_addc_co_u32_e64 v97, s[0:1], 0, v97, s[0:1]
	global_load_dwordx4 v[96:99], v[96:97], off offset:256
	s_waitcnt lgkmcnt(9)
	v_mfma_f32_32x32x16_bf16 v[52:67], v[108:111], v[116:119], v[52:67]
	s_add_u32 s12, s12, 0x80
	s_addc_u32 s13, s13, 0
	s_cmpk_eq_i32 s12, 0x700
	s_waitcnt lgkmcnt(0)
	s_barrier
	v_mfma_f32_32x32x16_bf16 v[20:35], v[108:111], v[120:123], v[20:35]
	v_mfma_f32_32x32x16_bf16 v[36:51], v[112:115], v[116:119], v[36:51]
	v_mfma_f32_32x32x16_bf16 v[4:19], v[112:115], v[120:123], v[4:19]
	s_cbranch_scc0 .LBB0_1401
	ds_read_b128 v[100:103], v106 offset:4608
	ds_read_b128 v[108:111], v1 offset:41472
	ds_read_b128 v[112:115], v106
	ds_read_b128 v[116:119], v106 offset:32
	ds_read_b128 v[120:123], v1 offset:36864
	ds_read_b128 v[124:127], v1 offset:36896
	s_waitcnt lgkmcnt(4)
	v_mfma_f32_32x32x16_bf16 v[4:19], v[100:103], v[108:111], v[4:19]
	v_add_u32_e32 v2, 0xd800, v0
	s_waitcnt lgkmcnt(1)
	v_mfma_f32_32x32x16_bf16 v[52:67], v[112:115], v[120:123], v[52:67]
	v_mfma_f32_32x32x16_bf16 v[20:35], v[112:115], v[108:111], v[20:35]
	v_mfma_f32_32x32x16_bf16 v[36:51], v[100:103], v[120:123], v[36:51]
	ds_read_b128 v[100:103], v106 offset:4640
	ds_read_b128 v[108:111], v1 offset:41504
	s_waitcnt lgkmcnt(2)
	v_mfma_f32_32x32x16_bf16 v[52:67], v[116:119], v[124:127], v[52:67]
	s_waitcnt lgkmcnt(0)
	v_mfma_f32_32x32x16_bf16 v[20:35], v[116:119], v[108:111], v[20:35]
	v_mfma_f32_32x32x16_bf16 v[36:51], v[100:103], v[124:127], v[36:51]
	v_mfma_f32_32x32x16_bf16 v[4:19], v[100:103], v[108:111], v[4:19]
	ds_read_b128 v[100:103], v106 offset:64
	ds_read_b128 v[108:111], v106 offset:4672
	ds_read_b128 v[112:115], v1 offset:36928
	ds_read_b128 v[116:119], v1 offset:41536
	s_waitcnt lgkmcnt(1)
	v_mfma_f32_32x32x16_bf16 v[52:67], v[100:103], v[112:115], v[52:67]
	s_waitcnt lgkmcnt(0)
	v_mfma_f32_32x32x16_bf16 v[20:35], v[100:103], v[116:119], v[20:35]
	v_mfma_f32_32x32x16_bf16 v[36:51], v[108:111], v[112:115], v[36:51]
	v_mfma_f32_32x32x16_bf16 v[4:19], v[108:111], v[116:119], v[4:19]
	ds_read_b128 v[100:103], v106 offset:96
	ds_read_b128 v[108:111], v106 offset:4704
	ds_read_b128 v[112:115], v1 offset:36960
	ds_read_b128 v[116:119], v1 offset:41568
	s_waitcnt vmcnt(7)
	ds_write_b128 v0, v[68:71] offset:18432
	s_waitcnt vmcnt(6)
	ds_write_b128 v0, v[72:75] offset:23040
	s_waitcnt vmcnt(5)
	ds_write_b128 v0, v[76:79] offset:27648
	s_waitcnt vmcnt(4)
	ds_write_b128 v0, v[80:83] offset:32256
	s_waitcnt vmcnt(3)
	ds_write_b128 v0, v[84:87] offset:55296
	s_waitcnt vmcnt(2)
	ds_write_b128 v0, v[88:91] offset:59904
	s_waitcnt vmcnt(1)
	ds_write_b128 v0, v[92:95] offset:64512
	s_waitcnt vmcnt(0)
	ds_write_b128 v2, v[96:99] offset:13824
	s_waitcnt lgkmcnt(0)
	s_barrier
; #define MFMA32(a, b, c) __builtin_amdgcn_mfma_f32_32x32x16_bf16((a), (b), (c), 0, 0, 0)
; DI uint32_t pack2(float a, float b) { f2_t v = {a, b}; bf2_t r = __builtin_convertvector(v, bf2_t); return __builtin_bit_cast(uint32_t, r); }
; DI float xor32(float v) { return __shfl_xor(v, 32); }
; DI void gemm128(const u16* __restrict__ W, int ldw, const u16* __restrict__ X, int ldx, int K, f32x16 (&acc)[2][2], char* smem) {
;     ...
;     for (int ks = 0; ks < 4; ++ks) {
;       bf16x8 a0 = *(const bf16x8*)&sw[buf][wn * 64 + r][ks * 16 + h * 8];
;       bf16x8 a1 = *(const bf16x8*)&sw[buf][wn * 64 + 32 + r][ks * 16 + h * 8];
;       bf16x8 b0 = *(const bf16x8*)&sx[buf][wm * 64 + r][ks * 16 + h * 8];
;       bf16x8 b1 = *(const bf16x8*)&sx[buf][wm * 64 + 32 + r][ks * 16 + h * 8];
;       acc[0][0] = MFMA32(a0, b0, acc[0][0]);
;       acc[0][1] = MFMA32(a0, b1, acc[0][1]);
;       acc[1][0] = MFMA32(a1, b0, acc[1][0]);
;       acc[1][1] = MFMA32(a1, b1, acc[1][1]);
; DI void phase_out(const Params& p, int layer, char* smem, int xcd, int loc, int nloc) {
;     ...
; #pragma unroll
;     for (int mi = 0; mi < 2; ++mi) {
;       const int m = m0 + wm * 64 + mi * 32 + r;
;       float ss = 0.f;
; #pragma unroll
;       for (int ni = 0; ni < 2; ++ni)
; #pragma unroll
;         for (int g = 0; g < 4; ++g) {
;           const int n4 = n0 + wn * 64 + ni * 32 + 8 * g + 4 * h;
;           float4 xo = *(const float4*)(xin + (size_t)m * 1024 + n4);
;           xo.x += acc[ni][mi][4 * g]; xo.y += acc[ni][mi][4 * g + 1]; xo.z += acc[ni][mi][4 * g + 2]; xo.w += acc[ni][mi][4 * g + 3];
;           *(float4*)(p.out + (size_t)m * 1024 + n4) = xo;
;           *(uint2*)(XB + (size_t)m * LDX + n4) = make_uint2(pack2(xo.x, xo.y), pack2(xo.z, xo.w));
;           ss += xo.x * xo.x + xo.y * xo.y + xo.z * xo.z + xo.w * xo.w;
;         }
;       ss += xor32(ss);
;       if (h == 0) XSS[(size_t)m * 16 + nt * 2 + wn] = ss;
	ds_read_b128 v[68:71], v106 offset:23040
	ds_read_b128 v[72:75], v1 offset:59904
	ds_read_b128 v[76:79], v106 offset:18432
	ds_read_b128 v[80:83], v106 offset:18464
	ds_read_b128 v[84:87], v1 offset:55296
	ds_read_b128 v[88:91], v1 offset:55328
	v_mfma_f32_32x32x16_bf16 v[52:67], v[100:103], v[112:115], v[52:67]
	v_and_b32_e32 v2, 64, v213
	v_add_u32_e32 v2, 64, v2
	v_or_b32_e32 v0, s30, v105
	v_mfma_f32_32x32x16_bf16 v[20:35], v[100:103], v[116:119], v[20:35]
	v_mfma_f32_32x32x16_bf16 v[36:51], v[108:111], v[112:115], v[36:51]
	v_mfma_f32_32x32x16_bf16 v[4:19], v[108:111], v[116:119], v[4:19]
	s_waitcnt lgkmcnt(1)
	v_mfma_f32_32x32x16_bf16 v[52:67], v[76:79], v[84:87], v[52:67]
	v_mfma_f32_32x32x16_bf16 v[20:35], v[76:79], v[72:75], v[20:35]
	v_mfma_f32_32x32x16_bf16 v[36:51], v[68:71], v[84:87], v[36:51]
	v_mfma_f32_32x32x16_bf16 v[4:19], v[68:71], v[72:75], v[4:19]
	ds_read_b128 v[68:71], v106 offset:23072
	ds_read_b128 v[72:75], v1 offset:59936
	s_waitcnt lgkmcnt(2)
	v_mfma_f32_32x32x16_bf16 v[52:67], v[80:83], v[88:91], v[52:67]
	s_waitcnt lgkmcnt(0)
	v_mfma_f32_32x32x16_bf16 v[20:35], v[80:83], v[72:75], v[20:35]
	v_mfma_f32_32x32x16_bf16 v[36:51], v[68:71], v[88:91], v[36:51]
	v_mfma_f32_32x32x16_bf16 v[4:19], v[68:71], v[72:75], v[4:19]
	ds_read_b128 v[68:71], v106 offset:18496
	ds_read_b128 v[72:75], v106 offset:23104
	ds_read_b128 v[76:79], v1 offset:55360
	ds_read_b128 v[80:83], v1 offset:59968
	s_waitcnt lgkmcnt(1)
	v_mfma_f32_32x32x16_bf16 v[52:67], v[68:71], v[76:79], v[52:67]
	s_waitcnt lgkmcnt(0)
	v_mfma_f32_32x32x16_bf16 v[20:35], v[68:71], v[80:83], v[20:35]
	v_mfma_f32_32x32x16_bf16 v[36:51], v[72:75], v[76:79], v[36:51]
	v_mfma_f32_32x32x16_bf16 v[4:19], v[72:75], v[80:83], v[4:19]
	ds_read_b128 v[68:71], v106 offset:18528
	ds_read_b128 v[72:75], v106 offset:23136
	ds_read_b128 v[76:79], v1 offset:55392
	ds_read_b128 v[80:83], v1 offset:60000
	v_xor_b32_e32 v1, 32, v213
	v_cmp_lt_i32_e64 s[0:1], v1, v2
	s_waitcnt lgkmcnt(0)
	s_barrier
	v_cndmask_b32_e64 v1, v213, v1, s[0:1]
	v_lshlrev_b32_e32 v2, 2, v1
	v_mfma_f32_32x32x16_bf16 v[52:67], v[68:71], v[76:79], v[52:67]
	v_ashrrev_i32_e32 v1, 31, v0
	s_lshl_b32 s0, s29, 1
	s_ashr_i32 s1, s0, 31
	s_lshl_b64 s[0:1], s[0:1], 2
	s_add_u32 s0, s16, s0
	s_addc_u32 s1, s18, s1
	v_mfma_f32_32x32x16_bf16 v[20:35], v[68:71], v[80:83], v[20:35]
	v_add_u32_e32 v68, s31, v104
	v_ashrrev_i32_e32 v69, 31, v68
	v_mov_b64_e32 v[70:71], s[22:23]
	v_mfma_f32_32x32x16_bf16 v[36:51], v[72:75], v[76:79], v[36:51]
	v_mfma_f32_32x32x16_bf16 v[4:19], v[72:75], v[80:83], v[4:19]
	v_lshlrev_b64 v[72:73], 12, v[68:69]
	v_lshl_add_u64 v[74:75], s[10:11], 0, v[72:73]
	v_mad_i64_i32 v[80:81], s[12:13], v68, s24, v[70:71]
	v_lshlrev_b64 v[70:71], 2, v[0:1]
	v_lshl_add_u64 v[74:75], v[74:75], 0, v[70:71]
	global_load_dwordx4 v[170:173], v[74:75], off
	global_load_dwordx4 v[174:177], v[74:75], off offset:32
	global_load_dwordx4 v[178:181], v[74:75], off offset:64
	global_load_dwordx4 v[182:185], v[74:75], off offset:96
	global_load_dwordx4 v[186:189], v[74:75], off offset:128
	global_load_dwordx4 v[190:193], v[74:75], off offset:160
	global_load_dwordx4 v[194:197], v[74:75], off offset:192
	global_load_dwordx4 v[198:201], v[74:75], off offset:224
	v_lshl_add_u64 v[72:73], s[92:93], 0, v[72:73]
	v_lshl_add_u64 v[72:73], v[72:73], 0, v[70:71]
	v_lshl_add_u64 v[80:81], v[0:1], 1, v[80:81]
	s_waitcnt vmcnt(0)
	v_mov_b64_e32 v[76:77], v[170:171]
	v_mov_b64_e32 v[78:79], v[172:173]
	v_pk_add_f32 v[76:77], v[52:53], v[76:77]
	v_pk_add_f32 v[78:79], v[54:55], v[78:79]
	v_cvt_pk_bf16_f32 v52, v76, v77
	v_cvt_pk_bf16_f32 v53, v78, v79
	global_store_dwordx4 v[72:73], v[76:79], off
	global_store_dwordx2 v[80:81], v[52:53], off
	v_pk_mul_f32 v[54:55], v[76:77], v[76:77]
	v_pk_mul_f32 v[52:53], v[78:79], v[78:79]
	v_mov_b64_e32 v[76:77], v[174:175]
	v_mov_b64_e32 v[78:79], v[176:177]
	v_pk_add_f32 v[76:77], v[56:57], v[76:77]
	v_pk_add_f32 v[78:79], v[58:59], v[78:79]
	v_cvt_pk_bf16_f32 v56, v76, v77
	v_cvt_pk_bf16_f32 v57, v78, v79
	global_store_dwordx4 v[72:73], v[76:79], off offset:32
	global_store_dwordx2 v[80:81], v[56:57], off offset:16
	v_pk_mul_f32 v[58:59], v[76:77], v[76:77]
	v_pk_mul_f32 v[56:57], v[78:79], v[78:79]
	v_mov_b64_e32 v[76:77], v[178:179]
	v_mov_b64_e32 v[78:79], v[180:181]
	v_pk_add_f32 v[76:77], v[60:61], v[76:77]
	v_pk_add_f32 v[78:79], v[62:63], v[78:79]
	v_cvt_pk_bf16_f32 v60, v76, v77
	v_cvt_pk_bf16_f32 v61, v78, v79
	global_store_dwordx4 v[72:73], v[76:79], off offset:64
	global_store_dwordx2 v[80:81], v[60:61], off offset:32
	v_pk_mul_f32 v[62:63], v[76:77], v[76:77]
	v_pk_mul_f32 v[60:61], v[78:79], v[78:79]
	v_mov_b64_e32 v[76:77], v[182:183]
	v_mov_b64_e32 v[78:79], v[184:185]
	v_pk_add_f32 v[76:77], v[64:65], v[76:77]
	v_pk_add_f32 v[78:79], v[66:67], v[78:79]
	v_cvt_pk_bf16_f32 v64, v76, v77
	v_cvt_pk_bf16_f32 v65, v78, v79
	global_store_dwordx4 v[72:73], v[76:79], off offset:96
	global_store_dwordx2 v[80:81], v[64:65], off offset:48
	v_pk_mul_f32 v[66:67], v[76:77], v[76:77]
	v_pk_mul_f32 v[64:65], v[78:79], v[78:79]
	v_mov_b64_e32 v[76:77], v[186:187]
	v_mov_b64_e32 v[78:79], v[188:189]
	v_pk_add_f32 v[36:37], v[36:37], v[76:77]
	v_pk_add_f32 v[38:39], v[38:39], v[78:79]
	v_cvt_pk_bf16_f32 v76, v36, v37
	v_cvt_pk_bf16_f32 v77, v38, v39
	global_store_dwordx4 v[72:73], v[36:39], off offset:128
	global_store_dwordx2 v[80:81], v[76:77], off offset:64
	v_pk_mul_f32 v[76:77], v[36:37], v[36:37]
	v_pk_mul_f32 v[78:79], v[38:39], v[38:39]
	v_mov_b64_e32 v[36:37], v[190:191]
	v_mov_b64_e32 v[38:39], v[192:193]
	v_pk_add_f32 v[36:37], v[40:41], v[36:37]
	v_pk_add_f32 v[38:39], v[42:43], v[38:39]
; DI uint32_t pack2(float a, float b) { f2_t v = {a, b}; bf2_t r = __builtin_convertvector(v, bf2_t); return __builtin_bit_cast(uint32_t, r); }
; DI float xor32(float v) { return __shfl_xor(v, 32); }
; DI void phase_out(const Params& p, int layer, char* smem, int xcd, int loc, int nloc) {
;     ...
;         for (int g = 0; g < 4; ++g) {
;           const int n4 = n0 + wn * 64 + ni * 32 + 8 * g + 4 * h;
;           float4 xo = *(const float4*)(xin + (size_t)m * 1024 + n4);
;           xo.x += acc[ni][mi][4 * g]; xo.y += acc[ni][mi][4 * g + 1]; xo.z += acc[ni][mi][4 * g + 2]; xo.w += acc[ni][mi][4 * g + 3];
;           *(float4*)(p.out + (size_t)m * 1024 + n4) = xo;
;           *(uint2*)(XB + (size_t)m * LDX + n4) = make_uint2(pack2(xo.x, xo.y), pack2(xo.z, xo.w));
;           ss += xo.x * xo.x + xo.y * xo.y + xo.z * xo.z + xo.w * xo.w;
;         }
;       ss += xor32(ss);
;       if (h == 0) XSS[(size_t)m * 16 + nt * 2 + wn] = ss;
	v_cvt_pk_bf16_f32 v40, v36, v37
	v_cvt_pk_bf16_f32 v41, v38, v39
	global_store_dwordx4 v[72:73], v[36:39], off offset:160
	global_store_dwordx2 v[80:81], v[40:41], off offset:80
	v_pk_mul_f32 v[40:41], v[36:37], v[36:37]
	v_pk_mul_f32 v[42:43], v[38:39], v[38:39]
	v_mov_b64_e32 v[36:37], v[194:195]
	v_mov_b64_e32 v[38:39], v[196:197]
	v_add_f32_e32 v40, v40, v41
	v_add_f32_e32 v40, v42, v40
	v_add_f32_e32 v40, v43, v40
	v_pk_add_f32 v[36:37], v[44:45], v[36:37]
	v_pk_add_f32 v[38:39], v[46:47], v[38:39]
	v_cvt_pk_bf16_f32 v44, v36, v37
	v_cvt_pk_bf16_f32 v45, v38, v39
	global_store_dwordx4 v[72:73], v[36:39], off offset:192
	global_store_dwordx2 v[80:81], v[44:45], off offset:96
	v_pk_mul_f32 v[44:45], v[36:37], v[36:37]
	v_pk_mul_f32 v[46:47], v[38:39], v[38:39]
	v_mov_b64_e32 v[36:37], v[198:199]
	v_mov_b64_e32 v[38:39], v[200:201]
	v_add_f32_e32 v41, v44, v45
	v_add_f32_e32 v41, v46, v41
	v_add_f32_e32 v41, v47, v41
	v_pk_add_f32 v[36:37], v[48:49], v[36:37]
	v_pk_add_f32 v[38:39], v[50:51], v[38:39]
	v_cvt_pk_bf16_f32 v48, v36, v37
	v_cvt_pk_bf16_f32 v49, v38, v39
	global_store_dwordx4 v[72:73], v[36:39], off offset:224
	global_store_dwordx2 v[80:81], v[48:49], off offset:112
	v_add_f32_e32 v48, v54, v55
	v_add_f32_e32 v49, v58, v59
	v_add_f32_e32 v48, v52, v48
	v_add_f32_e32 v49, v56, v49
	v_add_f32_e32 v48, v53, v48
	v_add_f32_e32 v49, v57, v49
	v_add_f32_e32 v48, v48, v49
	v_add_f32_e32 v49, v62, v63
	v_add_f32_e32 v49, v60, v49
	v_add_f32_e32 v49, v61, v49
	v_add_f32_e32 v48, v48, v49
	v_add_f32_e32 v49, v66, v67
	v_add_f32_e32 v49, v64, v49
	v_add_f32_e32 v49, v65, v49
	v_add_f32_e32 v48, v48, v49
	v_add_f32_e32 v49, v76, v77
	v_add_f32_e32 v49, v78, v49
	v_pk_mul_f32 v[36:37], v[36:37], v[36:37]
	v_add_f32_e32 v49, v79, v49
	v_pk_mul_f32 v[38:39], v[38:39], v[38:39]
	v_add_f32_e32 v48, v48, v49
	v_add_f32_e32 v36, v36, v37
	v_add_f32_e32 v40, v48, v40
	v_add_f32_e32 v36, v38, v36
	v_add_f32_e32 v40, v40, v41
	v_add_f32_e32 v36, v39, v36
	v_add_f32_e32 v36, v40, v36
	ds_bpermute_b32 v37, v2, v36
	s_and_saveexec_b64 s[12:13], vcc
	s_cbranch_execz .LBB0_1404
	v_lshlrev_b64 v[38:39], 6, v[68:69]
	v_lshl_add_u64 v[38:39], s[0:1], 0, v[38:39]
	s_waitcnt lgkmcnt(0)
	v_add_f32_e32 v36, v36, v37
	global_store_dword v[38:39], v36, off
; DI uint32_t pack2(float a, float b) { f2_t v = {a, b}; bf2_t r = __builtin_convertvector(v, bf2_t); return __builtin_bit_cast(uint32_t, r); }
; DI float xor32(float v) { return __shfl_xor(v, 32); }
; DI void phase_out(const Params& p, int layer, char* smem, int xcd, int loc, int nloc) {
;     ...
;     for (int mi = 0; mi < 2; ++mi) {
;       const int m = m0 + wm * 64 + mi * 32 + r;
;       float ss = 0.f;
; #pragma unroll
;       for (int ni = 0; ni < 2; ++ni)
; #pragma unroll
;         for (int g = 0; g < 4; ++g) {
;           const int n4 = n0 + wn * 64 + ni * 32 + 8 * g + 4 * h;
;           float4 xo = *(const float4*)(xin + (size_t)m * 1024 + n4);
;           xo.x += acc[ni][mi][4 * g]; xo.y += acc[ni][mi][4 * g + 1]; xo.z += acc[ni][mi][4 * g + 2]; xo.w += acc[ni][mi][4 * g + 3];
;           *(float4*)(p.out + (size_t)m * 1024 + n4) = xo;
;           *(uint2*)(XB + (size_t)m * LDX + n4) = make_uint2(pack2(xo.x, xo.y), pack2(xo.z, xo.w));
;           ss += xo.x * xo.x + xo.y * xo.y + xo.z * xo.z + xo.w * xo.w;
;         }
;       ss += xor32(ss);
;       if (h == 0) XSS[(size_t)m * 16 + nt * 2 + wn] = ss;
.LBB0_1404:
	s_or_b64 exec, exec, s[12:13]
	v_or_b32_e32 v36, 32, v68
	s_waitcnt lgkmcnt(0)
	v_ashrrev_i32_e32 v37, 31, v36
	v_lshlrev_b64 v[38:39], 12, v[36:37]
	v_lshl_add_u64 v[40:41], s[10:11], 0, v[38:39]
	v_mov_b64_e32 v[42:43], s[22:23]
	v_lshl_add_u64 v[40:41], v[40:41], 0, v[70:71]
	v_mad_i64_i32 v[46:47], s[12:13], v36, s24, v[42:43]
	global_load_dwordx4 v[170:173], v[40:41], off
	global_load_dwordx4 v[174:177], v[40:41], off offset:32
	global_load_dwordx4 v[178:181], v[40:41], off offset:64
	global_load_dwordx4 v[182:185], v[40:41], off offset:96
	global_load_dwordx4 v[186:189], v[40:41], off offset:128
	global_load_dwordx4 v[190:193], v[40:41], off offset:160
	global_load_dwordx4 v[194:197], v[40:41], off offset:192
	global_load_dwordx4 v[198:201], v[40:41], off offset:224
	v_lshl_add_u64 v[38:39], s[92:93], 0, v[38:39]
	v_lshl_add_u64 v[38:39], v[38:39], 0, v[70:71]
	v_lshl_add_u64 v[0:1], v[0:1], 1, v[46:47]
	s_waitcnt vmcnt(0)
	v_mov_b64_e32 v[42:43], v[170:171]
	v_mov_b64_e32 v[44:45], v[172:173]
	v_pk_add_f32 v[20:21], v[20:21], v[42:43]
	v_pk_add_f32 v[22:23], v[22:23], v[44:45]
	v_cvt_pk_bf16_f32 v42, v20, v21
	v_cvt_pk_bf16_f32 v43, v22, v23
	global_store_dwordx4 v[38:39], v[20:23], off
	global_store_dwordx2 v[0:1], v[42:43], off
	v_pk_mul_f32 v[42:43], v[20:21], v[20:21]
	v_pk_mul_f32 v[44:45], v[22:23], v[22:23]
	v_mov_b64_e32 v[20:21], v[174:175]
	v_mov_b64_e32 v[22:23], v[176:177]
	v_pk_add_f32 v[20:21], v[24:25], v[20:21]
	v_pk_add_f32 v[22:23], v[26:27], v[22:23]
	v_cvt_pk_bf16_f32 v24, v20, v21
	v_cvt_pk_bf16_f32 v25, v22, v23
	global_store_dwordx4 v[38:39], v[20:23], off offset:32
	global_store_dwordx2 v[0:1], v[24:25], off offset:16
	v_pk_mul_f32 v[24:25], v[20:21], v[20:21]
	v_pk_mul_f32 v[26:27], v[22:23], v[22:23]
	v_mov_b64_e32 v[20:21], v[178:179]
	v_mov_b64_e32 v[22:23], v[180:181]
	v_pk_add_f32 v[20:21], v[28:29], v[20:21]
	v_pk_add_f32 v[22:23], v[30:31], v[22:23]
	v_cvt_pk_bf16_f32 v28, v20, v21
	v_cvt_pk_bf16_f32 v29, v22, v23
	global_store_dwordx4 v[38:39], v[20:23], off offset:64
	global_store_dwordx2 v[0:1], v[28:29], off offset:32
	v_pk_mul_f32 v[28:29], v[20:21], v[20:21]
	v_pk_mul_f32 v[30:31], v[22:23], v[22:23]
	v_mov_b64_e32 v[20:21], v[182:183]
	v_mov_b64_e32 v[22:23], v[184:185]
	v_pk_add_f32 v[20:21], v[32:33], v[20:21]
	v_pk_add_f32 v[22:23], v[34:35], v[22:23]
	v_cvt_pk_bf16_f32 v32, v20, v21
	v_cvt_pk_bf16_f32 v33, v22, v23
	global_store_dwordx4 v[38:39], v[20:23], off offset:96
	global_store_dwordx2 v[0:1], v[32:33], off offset:48
	v_pk_mul_f32 v[32:33], v[20:21], v[20:21]
	v_pk_mul_f32 v[34:35], v[22:23], v[22:23]
	v_mov_b64_e32 v[20:21], v[186:187]
	v_mov_b64_e32 v[22:23], v[188:189]
	v_pk_add_f32 v[4:5], v[4:5], v[20:21]
	v_pk_add_f32 v[6:7], v[6:7], v[22:23]
	v_cvt_pk_bf16_f32 v20, v4, v5
	v_cvt_pk_bf16_f32 v21, v6, v7
	global_store_dwordx4 v[38:39], v[4:7], off offset:128
	global_store_dwordx2 v[0:1], v[20:21], off offset:64
	v_pk_mul_f32 v[20:21], v[4:5], v[4:5]
	v_pk_mul_f32 v[22:23], v[6:7], v[6:7]
	v_mov_b64_e32 v[4:5], v[190:191]
	v_mov_b64_e32 v[6:7], v[192:193]
	v_pk_add_f32 v[4:5], v[8:9], v[4:5]
	v_pk_add_f32 v[6:7], v[10:11], v[6:7]
	v_cvt_pk_bf16_f32 v8, v4, v5
	v_cvt_pk_bf16_f32 v9, v6, v7
	global_store_dwordx4 v[38:39], v[4:7], off offset:160
	global_store_dwordx2 v[0:1], v[8:9], off offset:80
	v_pk_mul_f32 v[8:9], v[4:5], v[4:5]
	v_pk_mul_f32 v[10:11], v[6:7], v[6:7]
	v_mov_b64_e32 v[4:5], v[194:195]
	v_mov_b64_e32 v[6:7], v[196:197]
	v_pk_add_f32 v[4:5], v[12:13], v[4:5]
	v_pk_add_f32 v[6:7], v[14:15], v[6:7]
	v_cvt_pk_bf16_f32 v12, v4, v5
	v_cvt_pk_bf16_f32 v13, v6, v7
	global_store_dwordx4 v[38:39], v[4:7], off offset:192
	global_store_dwordx2 v[0:1], v[12:13], off offset:96
	v_pk_mul_f32 v[12:13], v[4:5], v[4:5]
	v_pk_mul_f32 v[14:15], v[6:7], v[6:7]
	v_mov_b64_e32 v[4:5], v[198:199]
	v_mov_b64_e32 v[6:7], v[200:201]
	v_pk_add_f32 v[4:5], v[16:17], v[4:5]
	v_pk_add_f32 v[6:7], v[18:19], v[6:7]
	v_cvt_pk_bf16_f32 v16, v4, v5
	v_cvt_pk_bf16_f32 v17, v6, v7
	global_store_dwordx4 v[38:39], v[4:7], off offset:224
	global_store_dwordx2 v[0:1], v[16:17], off offset:112
	v_pk_mul_f32 v[0:1], v[4:5], v[4:5]
	v_pk_mul_f32 v[4:5], v[6:7], v[6:7]
	v_add_f32_e32 v6, v42, v43
	v_add_f32_e32 v7, v24, v25
	v_add_f32_e32 v6, v44, v6
	v_add_f32_e32 v7, v26, v7
	v_add_f32_e32 v6, v45, v6
	v_add_f32_e32 v7, v27, v7
	v_add_f32_e32 v6, v6, v7
	v_add_f32_e32 v7, v28, v29
	v_add_f32_e32 v7, v30, v7
	v_add_f32_e32 v7, v31, v7
	v_add_f32_e32 v6, v6, v7
	v_add_f32_e32 v7, v32, v33
	v_add_f32_e32 v7, v34, v7
	v_add_f32_e32 v7, v35, v7
	v_add_f32_e32 v6, v6, v7
	v_add_f32_e32 v7, v20, v21
	v_add_f32_e32 v7, v22, v7
	v_add_f32_e32 v7, v23, v7
	v_add_f32_e32 v6, v6, v7
	v_add_f32_e32 v7, v8, v9
	v_add_f32_e32 v7, v10, v7
	v_add_f32_e32 v7, v11, v7
	v_add_f32_e32 v6, v6, v7
	v_add_f32_e32 v7, v12, v13
	v_add_f32_e32 v7, v14, v7
	v_add_f32_e32 v0, v0, v1
	v_add_f32_e32 v7, v15, v7
	v_add_f32_e32 v0, v4, v0
	v_add_f32_e32 v6, v6, v7
	v_add_f32_e32 v0, v5, v0
	v_add_f32_e32 v0, v6, v0
	ds_bpermute_b32 v1, v2, v0
	s_and_saveexec_b64 s[12:13], vcc
	s_cbranch_execz .LBB0_1399
	v_lshlrev_b64 v[4:5], 6, v[36:37]
	v_lshl_add_u64 v[4:5], s[0:1], 0, v[4:5]
	s_waitcnt lgkmcnt(0)
	v_add_f32_e32 v0, v0, v1
	global_store_dword v[4:5], v0, off
	s_branch .LBB0_1399
